# v47 plus rstd_phase de-serialised: the 32 partial-sum loads of a row issued back to back into 32 registers instead of load / vmcnt(0) / add one at a time (same summation order)
# speedup vs baseline: 1.0050x; 1.0028x over previous
; __device__ __forceinline__ void rstd_phase(const Frame& F, KArgs* A_, int nidx) {
;     ...
;     for (int r = gw * 64 + lane; r < MT; r += NGW * 64) { float s = 0.f;
; #pragma unroll 8
;         for (int k = 0; k < 32; ++k) s += part[(size_t)k * MT + r];
;         rstd[r] = rsqrtf(s * (1.0f / DM) + EPS); }
.LBB0_1716:
	v_add_co_u32_e32 v6, vcc, 0x2c5c8000, v4
	s_nop 1
	v_addc_co_u32_e32 v7, vcc, 0, v5, vcc
	global_load_dword v10, v[6:7], off
	v_add_co_u32_e32 v8, vcc, 0x12000, v6
	s_nop 1
	v_addc_co_u32_e32 v9, vcc, 0, v7, vcc
	global_load_dword v11, v[8:9], off
	v_add_co_u32_e32 v8, vcc, 0x24000, v6
	s_nop 1
	v_addc_co_u32_e32 v9, vcc, 0, v7, vcc
	global_load_dword v12, v[8:9], off
	v_add_co_u32_e32 v8, vcc, 0x36000, v6
	s_nop 1
	v_addc_co_u32_e32 v9, vcc, 0, v7, vcc
	global_load_dword v13, v[8:9], off
	v_add_co_u32_e32 v8, vcc, 0x48000, v6
	s_nop 1
	v_addc_co_u32_e32 v9, vcc, 0, v7, vcc
	global_load_dword v14, v[8:9], off
	v_add_co_u32_e32 v8, vcc, 0x5a000, v6
	s_nop 1
	v_addc_co_u32_e32 v9, vcc, 0, v7, vcc
	global_load_dword v15, v[8:9], off
	v_add_co_u32_e32 v8, vcc, 0x6c000, v6
	s_nop 1
	v_addc_co_u32_e32 v9, vcc, 0, v7, vcc
	global_load_dword v16, v[8:9], off
	v_add_co_u32_e32 v8, vcc, 0x7e000, v6
	s_nop 1
	v_addc_co_u32_e32 v9, vcc, 0, v7, vcc
	global_load_dword v17, v[8:9], off
	v_add_co_u32_e32 v8, vcc, 0x90000, v6
	s_nop 1
	v_addc_co_u32_e32 v9, vcc, 0, v7, vcc
	global_load_dword v18, v[8:9], off
	v_add_co_u32_e32 v8, vcc, 0xa2000, v6
	s_nop 1
	v_addc_co_u32_e32 v9, vcc, 0, v7, vcc
	global_load_dword v19, v[8:9], off
	v_add_co_u32_e32 v8, vcc, 0xb4000, v6
	s_nop 1
	v_addc_co_u32_e32 v9, vcc, 0, v7, vcc
	global_load_dword v20, v[8:9], off
	v_add_co_u32_e32 v8, vcc, 0xc6000, v6
	s_nop 1
	v_addc_co_u32_e32 v9, vcc, 0, v7, vcc
	global_load_dword v21, v[8:9], off
	v_add_co_u32_e32 v8, vcc, 0xd8000, v6
	s_nop 1
	v_addc_co_u32_e32 v9, vcc, 0, v7, vcc
	global_load_dword v22, v[8:9], off
	v_add_co_u32_e32 v8, vcc, 0xea000, v6
	s_nop 1
	v_addc_co_u32_e32 v9, vcc, 0, v7, vcc
	global_load_dword v23, v[8:9], off
	v_add_co_u32_e32 v8, vcc, 0xfc000, v6
	s_nop 1
	v_addc_co_u32_e32 v9, vcc, 0, v7, vcc
	global_load_dword v24, v[8:9], off
	v_add_co_u32_e32 v8, vcc, 0x10e000, v6
	s_nop 1
	v_addc_co_u32_e32 v9, vcc, 0, v7, vcc
	global_load_dword v25, v[8:9], off
	v_add_co_u32_e32 v8, vcc, 0x120000, v6
	s_nop 1
	v_addc_co_u32_e32 v9, vcc, 0, v7, vcc
	global_load_dword v26, v[8:9], off
	v_add_co_u32_e32 v8, vcc, 0x132000, v6
	s_nop 1
	v_addc_co_u32_e32 v9, vcc, 0, v7, vcc
	global_load_dword v27, v[8:9], off
	v_add_co_u32_e32 v8, vcc, 0x144000, v6
	s_nop 1
	v_addc_co_u32_e32 v9, vcc, 0, v7, vcc
	global_load_dword v28, v[8:9], off
	v_add_co_u32_e32 v8, vcc, 0x156000, v6
	s_nop 1
	v_addc_co_u32_e32 v9, vcc, 0, v7, vcc
	global_load_dword v29, v[8:9], off
	v_add_co_u32_e32 v8, vcc, 0x168000, v6
	s_nop 1
	v_addc_co_u32_e32 v9, vcc, 0, v7, vcc
	global_load_dword v30, v[8:9], off
	v_add_co_u32_e32 v8, vcc, 0x17a000, v6
	s_nop 1
	v_addc_co_u32_e32 v9, vcc, 0, v7, vcc
	global_load_dword v31, v[8:9], off
	v_add_co_u32_e32 v8, vcc, 0x18c000, v6
	s_nop 1
	v_addc_co_u32_e32 v9, vcc, 0, v7, vcc
	global_load_dword v32, v[8:9], off
	v_add_co_u32_e32 v8, vcc, 0x19e000, v6
	s_nop 1
	v_addc_co_u32_e32 v9, vcc, 0, v7, vcc
	global_load_dword v33, v[8:9], off
	v_add_co_u32_e32 v8, vcc, 0x1b0000, v6
	s_nop 1
	v_addc_co_u32_e32 v9, vcc, 0, v7, vcc
	global_load_dword v34, v[8:9], off
	v_add_co_u32_e32 v8, vcc, 0x1c2000, v6
	s_nop 1
	v_addc_co_u32_e32 v9, vcc, 0, v7, vcc
	global_load_dword v35, v[8:9], off
	v_add_co_u32_e32 v8, vcc, 0x1d4000, v6
	s_nop 1
	v_addc_co_u32_e32 v9, vcc, 0, v7, vcc
	global_load_dword v36, v[8:9], off
	v_add_co_u32_e32 v8, vcc, 0x1e6000, v6
	s_nop 1
	v_addc_co_u32_e32 v9, vcc, 0, v7, vcc
	global_load_dword v37, v[8:9], off
	v_add_co_u32_e32 v8, vcc, 0x1f8000, v6
	s_nop 1
	v_addc_co_u32_e32 v9, vcc, 0, v7, vcc
	global_load_dword v38, v[8:9], off
	v_add_co_u32_e32 v8, vcc, 0x20a000, v6
	s_nop 1
	v_addc_co_u32_e32 v9, vcc, 0, v7, vcc
	global_load_dword v39, v[8:9], off
	v_add_co_u32_e32 v8, vcc, 0x21c000, v6
	s_nop 1
	v_addc_co_u32_e32 v9, vcc, 0, v7, vcc
	global_load_dword v40, v[8:9], off
	v_add_co_u32_e32 v8, vcc, 0x22e000, v6
	s_nop 1
	v_addc_co_u32_e32 v9, vcc, 0, v7, vcc
	global_load_dword v41, v[8:9], off
	s_waitcnt vmcnt(31)
	v_add_f32_e32 v0, v0, v10
	s_waitcnt vmcnt(30)
	v_add_f32_e32 v0, v0, v11
	s_waitcnt vmcnt(29)
	v_add_f32_e32 v0, v0, v12
	s_waitcnt vmcnt(28)
	v_add_f32_e32 v0, v0, v13
	s_waitcnt vmcnt(27)
	v_add_f32_e32 v0, v0, v14
	s_waitcnt vmcnt(26)
	v_add_f32_e32 v0, v0, v15
	s_waitcnt vmcnt(25)
	v_add_f32_e32 v0, v0, v16
	s_waitcnt vmcnt(24)
	v_add_f32_e32 v0, v0, v17
	s_waitcnt vmcnt(23)
	v_add_f32_e32 v0, v0, v18
	s_waitcnt vmcnt(22)
	v_add_f32_e32 v0, v0, v19
	s_waitcnt vmcnt(21)
	v_add_f32_e32 v0, v0, v20
	s_waitcnt vmcnt(20)
	v_add_f32_e32 v0, v0, v21
	s_waitcnt vmcnt(19)
	v_add_f32_e32 v0, v0, v22
	s_waitcnt vmcnt(18)
	v_add_f32_e32 v0, v0, v23
	s_waitcnt vmcnt(17)
	v_add_f32_e32 v0, v0, v24
	s_waitcnt vmcnt(16)
	v_add_f32_e32 v0, v0, v25
	s_waitcnt vmcnt(15)
	v_add_f32_e32 v0, v0, v26
	s_waitcnt vmcnt(14)
	v_add_f32_e32 v0, v0, v27
	s_waitcnt vmcnt(13)
	v_add_f32_e32 v0, v0, v28
	s_waitcnt vmcnt(12)
	v_add_f32_e32 v0, v0, v29
	s_waitcnt vmcnt(11)
	v_add_f32_e32 v0, v0, v30
	s_waitcnt vmcnt(10)
	v_add_f32_e32 v0, v0, v31
	s_waitcnt vmcnt(9)
	v_add_f32_e32 v0, v0, v32
	s_waitcnt vmcnt(8)
	v_add_f32_e32 v0, v0, v33
	s_waitcnt vmcnt(7)
	v_add_f32_e32 v0, v0, v34
	s_waitcnt vmcnt(6)
	v_add_f32_e32 v0, v0, v35
	s_waitcnt vmcnt(5)
	v_add_f32_e32 v0, v0, v36
	s_waitcnt vmcnt(4)
	v_add_f32_e32 v0, v0, v37
	s_waitcnt vmcnt(3)
	v_add_f32_e32 v0, v0, v38
	s_waitcnt vmcnt(2)
	v_add_f32_e32 v0, v0, v39
	s_waitcnt vmcnt(1)
	v_add_f32_e32 v0, v0, v40
	s_waitcnt vmcnt(0)
	v_add_f32_e32 v0, v0, v41
	v_fmamk_f32 v0, v0, 0x3a000000, v250
	s_mov_b32 s2, 0x800000
	v_cmp_gt_f32_e32 vcc, s2, v0
	v_mul_f32_e32 v6, 0x4b800000, v0
	v_ashrrev_i32_e32 v3, 31, v2
	v_cndmask_b32_e32 v0, v0, v6, vcc
	v_rsq_f32_e32 v0, v0
	v_lshl_add_u64 v[4:5], v[4:5], 0, s[10:11]
	v_mul_f32_e32 v6, 0x45800000, v0
	v_cndmask_b32_e32 v0, v0, v6, vcc
	v_lshl_add_u64 v[6:7], v[2:3], 2, s[6:7]
	v_add_u32_e32 v2, s8, v2
	v_cmp_lt_i32_e32 vcc, s38, v2
	s_or_b64 s[12:13], vcc, s[12:13]
	global_store_dword v[6:7], v0, off
	s_andn2_b64 exec, exec, s[12:13]
	s_cbranch_execnz .LBB0_1715

; __device__ __forceinline__ void rstd_phase(const Frame& F, KArgs* A_, int nidx) {
;     ...
;     for (int r = gw * 64 + lane; r < MT; r += NGW * 64) { float s = 0.f;
; #pragma unroll 8
;         for (int k = 0; k < 32; ++k) s += part[(size_t)k * MT + r];
;         rstd[r] = rsqrtf(s * (1.0f / DM) + EPS); }
.LBB0_2225:
	v_add_co_u32_e32 v6, vcc, 0x2c808000, v4
	s_nop 1
	v_addc_co_u32_e32 v7, vcc, 0, v5, vcc
	global_load_dword v10, v[6:7], off
	v_add_co_u32_e32 v8, vcc, 0x12000, v6
	s_nop 1
	v_addc_co_u32_e32 v9, vcc, 0, v7, vcc
	global_load_dword v11, v[8:9], off
	v_add_co_u32_e32 v8, vcc, 0x24000, v6
	s_nop 1
	v_addc_co_u32_e32 v9, vcc, 0, v7, vcc
	global_load_dword v12, v[8:9], off
	v_add_co_u32_e32 v8, vcc, 0x36000, v6
	s_nop 1
	v_addc_co_u32_e32 v9, vcc, 0, v7, vcc
	global_load_dword v13, v[8:9], off
	v_add_co_u32_e32 v8, vcc, 0x48000, v6
	s_nop 1
	v_addc_co_u32_e32 v9, vcc, 0, v7, vcc
	global_load_dword v14, v[8:9], off
	v_add_co_u32_e32 v8, vcc, 0x5a000, v6
	s_nop 1
	v_addc_co_u32_e32 v9, vcc, 0, v7, vcc
	global_load_dword v15, v[8:9], off
	v_add_co_u32_e32 v8, vcc, 0x6c000, v6
	s_nop 1
	v_addc_co_u32_e32 v9, vcc, 0, v7, vcc
	global_load_dword v16, v[8:9], off
	v_add_co_u32_e32 v8, vcc, 0x7e000, v6
	s_nop 1
	v_addc_co_u32_e32 v9, vcc, 0, v7, vcc
	global_load_dword v17, v[8:9], off
	v_add_co_u32_e32 v8, vcc, 0x90000, v6
	s_nop 1
	v_addc_co_u32_e32 v9, vcc, 0, v7, vcc
	global_load_dword v18, v[8:9], off
	v_add_co_u32_e32 v8, vcc, 0xa2000, v6
	s_nop 1
	v_addc_co_u32_e32 v9, vcc, 0, v7, vcc
	global_load_dword v19, v[8:9], off
	v_add_co_u32_e32 v8, vcc, 0xb4000, v6
	s_nop 1
	v_addc_co_u32_e32 v9, vcc, 0, v7, vcc
	global_load_dword v20, v[8:9], off
	v_add_co_u32_e32 v8, vcc, 0xc6000, v6
	s_nop 1
	v_addc_co_u32_e32 v9, vcc, 0, v7, vcc
	global_load_dword v21, v[8:9], off
	v_add_co_u32_e32 v8, vcc, 0xd8000, v6
	s_nop 1
	v_addc_co_u32_e32 v9, vcc, 0, v7, vcc
	global_load_dword v22, v[8:9], off
	v_add_co_u32_e32 v8, vcc, 0xea000, v6
	s_nop 1
	v_addc_co_u32_e32 v9, vcc, 0, v7, vcc
	global_load_dword v23, v[8:9], off
	v_add_co_u32_e32 v8, vcc, 0xfc000, v6
	s_nop 1
	v_addc_co_u32_e32 v9, vcc, 0, v7, vcc
	global_load_dword v24, v[8:9], off
	v_add_co_u32_e32 v8, vcc, 0x10e000, v6
	s_nop 1
	v_addc_co_u32_e32 v9, vcc, 0, v7, vcc
	global_load_dword v25, v[8:9], off
	v_add_co_u32_e32 v8, vcc, 0x120000, v6
	s_nop 1
	v_addc_co_u32_e32 v9, vcc, 0, v7, vcc
	global_load_dword v26, v[8:9], off
	v_add_co_u32_e32 v8, vcc, 0x132000, v6
	s_nop 1
	v_addc_co_u32_e32 v9, vcc, 0, v7, vcc
	global_load_dword v27, v[8:9], off
	v_add_co_u32_e32 v8, vcc, 0x144000, v6
	s_nop 1
	v_addc_co_u32_e32 v9, vcc, 0, v7, vcc
	global_load_dword v28, v[8:9], off
	v_add_co_u32_e32 v8, vcc, 0x156000, v6
	s_nop 1
	v_addc_co_u32_e32 v9, vcc, 0, v7, vcc
	global_load_dword v29, v[8:9], off
	v_add_co_u32_e32 v8, vcc, 0x168000, v6
	s_nop 1
	v_addc_co_u32_e32 v9, vcc, 0, v7, vcc
	global_load_dword v30, v[8:9], off
	v_add_co_u32_e32 v8, vcc, 0x17a000, v6
	s_nop 1
	v_addc_co_u32_e32 v9, vcc, 0, v7, vcc
	global_load_dword v31, v[8:9], off
	v_add_co_u32_e32 v8, vcc, 0x18c000, v6
	s_nop 1
	v_addc_co_u32_e32 v9, vcc, 0, v7, vcc
	global_load_dword v32, v[8:9], off
	v_add_co_u32_e32 v8, vcc, 0x19e000, v6
	s_nop 1
	v_addc_co_u32_e32 v9, vcc, 0, v7, vcc
	global_load_dword v33, v[8:9], off
	v_add_co_u32_e32 v8, vcc, 0x1b0000, v6
	s_nop 1
	v_addc_co_u32_e32 v9, vcc, 0, v7, vcc
	global_load_dword v34, v[8:9], off
	v_add_co_u32_e32 v8, vcc, 0x1c2000, v6
	s_nop 1
	v_addc_co_u32_e32 v9, vcc, 0, v7, vcc
	global_load_dword v35, v[8:9], off
	v_add_co_u32_e32 v8, vcc, 0x1d4000, v6
	s_nop 1
	v_addc_co_u32_e32 v9, vcc, 0, v7, vcc
	global_load_dword v36, v[8:9], off
	v_add_co_u32_e32 v8, vcc, 0x1e6000, v6
	s_nop 1
	v_addc_co_u32_e32 v9, vcc, 0, v7, vcc
	global_load_dword v37, v[8:9], off
	v_add_co_u32_e32 v8, vcc, 0x1f8000, v6
	s_nop 1
	v_addc_co_u32_e32 v9, vcc, 0, v7, vcc
	global_load_dword v38, v[8:9], off
	v_add_co_u32_e32 v8, vcc, 0x20a000, v6
	s_nop 1
	v_addc_co_u32_e32 v9, vcc, 0, v7, vcc
	global_load_dword v39, v[8:9], off
	v_add_co_u32_e32 v8, vcc, 0x21c000, v6
	s_nop 1
	v_addc_co_u32_e32 v9, vcc, 0, v7, vcc
	global_load_dword v40, v[8:9], off
	v_add_co_u32_e32 v8, vcc, 0x22e000, v6
	s_nop 1
	v_addc_co_u32_e32 v9, vcc, 0, v7, vcc
	global_load_dword v41, v[8:9], off
	s_waitcnt vmcnt(31)
	v_add_f32_e32 v0, v0, v10
	s_waitcnt vmcnt(30)
	v_add_f32_e32 v0, v0, v11
	s_waitcnt vmcnt(29)
	v_add_f32_e32 v0, v0, v12
	s_waitcnt vmcnt(28)
	v_add_f32_e32 v0, v0, v13
	s_waitcnt vmcnt(27)
	v_add_f32_e32 v0, v0, v14
	s_waitcnt vmcnt(26)
	v_add_f32_e32 v0, v0, v15
	s_waitcnt vmcnt(25)
	v_add_f32_e32 v0, v0, v16
	s_waitcnt vmcnt(24)
	v_add_f32_e32 v0, v0, v17
	s_waitcnt vmcnt(23)
	v_add_f32_e32 v0, v0, v18
	s_waitcnt vmcnt(22)
	v_add_f32_e32 v0, v0, v19
	s_waitcnt vmcnt(21)
	v_add_f32_e32 v0, v0, v20
	s_waitcnt vmcnt(20)
	v_add_f32_e32 v0, v0, v21
	s_waitcnt vmcnt(19)
	v_add_f32_e32 v0, v0, v22
	s_waitcnt vmcnt(18)
	v_add_f32_e32 v0, v0, v23
	s_waitcnt vmcnt(17)
	v_add_f32_e32 v0, v0, v24
	s_waitcnt vmcnt(16)
	v_add_f32_e32 v0, v0, v25
	s_waitcnt vmcnt(15)
	v_add_f32_e32 v0, v0, v26
	s_waitcnt vmcnt(14)
	v_add_f32_e32 v0, v0, v27
	s_waitcnt vmcnt(13)
	v_add_f32_e32 v0, v0, v28
	s_waitcnt vmcnt(12)
	v_add_f32_e32 v0, v0, v29
	s_waitcnt vmcnt(11)
	v_add_f32_e32 v0, v0, v30
	s_waitcnt vmcnt(10)
	v_add_f32_e32 v0, v0, v31
	s_waitcnt vmcnt(9)
	v_add_f32_e32 v0, v0, v32
	s_waitcnt vmcnt(8)
	v_add_f32_e32 v0, v0, v33
	s_waitcnt vmcnt(7)
	v_add_f32_e32 v0, v0, v34
	s_waitcnt vmcnt(6)
	v_add_f32_e32 v0, v0, v35
	s_waitcnt vmcnt(5)
	v_add_f32_e32 v0, v0, v36
	s_waitcnt vmcnt(4)
	v_add_f32_e32 v0, v0, v37
	s_waitcnt vmcnt(3)
	v_add_f32_e32 v0, v0, v38
	s_waitcnt vmcnt(2)
	v_add_f32_e32 v0, v0, v39
	s_waitcnt vmcnt(1)
	v_add_f32_e32 v0, v0, v40
	s_waitcnt vmcnt(0)
	v_add_f32_e32 v0, v0, v41
	v_fmamk_f32 v0, v0, 0x3a000000, v250
	s_mov_b32 s2, 0x800000
	v_cmp_gt_f32_e32 vcc, s2, v0
	v_mul_f32_e32 v6, 0x4b800000, v0
	v_ashrrev_i32_e32 v3, 31, v2
	v_cndmask_b32_e32 v0, v0, v6, vcc
	v_rsq_f32_e32 v0, v0
	v_lshl_add_u64 v[4:5], v[4:5], 0, s[8:9]
	v_mul_f32_e32 v6, 0x45800000, v0
	v_cndmask_b32_e32 v0, v0, v6, vcc
	v_lshl_add_u64 v[6:7], v[2:3], 2, s[4:5]
	v_add_u32_e32 v2, s6, v2
	v_cmp_lt_i32_e32 vcc, s38, v2
	s_or_b64 s[10:11], vcc, s[10:11]
	global_store_dword v[6:7], v0, off
	s_andn2_b64 exec, exec, s[10:11]
	s_cbranch_execnz .LBB0_2224
